# attention: the 16 packed f32 bias adds per step split into 32 scalar adds (packed VOP3P fp32 is dearer than two singles here)
# speedup vs baseline: 1.0005x; 1.0005x over previous
; #define WAIT_BAR(N) asm volatile("s_waitcnt vmcnt(" #N ") lgkmcnt(0)\n\ts_barrier":::"memory")
;   #define DMA_K(t,slot) glds16(ksrc+(long)(t)*KVBLK*DM,(unsigned)__builtin_amdgcn_readfirstlane(kdst+(slot)))
;   #define DMA_V(t,slot) glds16(vsrc+(long)(t)*KVBLK*DM,(unsigned)__builtin_amdgcn_readfirstlane(vdst+(slot)))
;   #define CMASK(P0,P1,t) do{int jb_=(t)-(NT-4); if(jb_>=0){int q_=qrel,h_=hi; asm volatile("":"+v"(q_),"+v"(h_)); cmask(P0,P1,jb_,q_,h_);}}while(0)
;   #define CMASK(P0,P1,t) do{}while(0)
;   #define CMASK(P0,P1,t) do{int jb_=(t)-(NT-4); if(jb_>=0){int q_=qrel,h_=hi; asm volatile("":"+v"(q_),"+v"(h_)); cmask(P0,P1,jb_,q_,h_);}}while(0)
; template<int THRL> __device__ __forceinline__ void attn_unit(int b,int h,int qb,const bf16*Q,const bf16*__restrict__ K,const bf16*__restrict__ V,bf16*O,char*shm,const int wv){
;     ...
;   const long rowbase=(long)b*SEQ; const int q0=qb*QB;
;   const bf16*Qw=Q+(rowbase+q0+wid*QBLK)*DM+h*D;
;   const bf16*Kh=K+rowbase*DM+h*D,*Vh=V+rowbase*DM+h*D;
;   const unsigned lds0=(unsigned)(uintptr_t)shm;
;   float*wsf=(float*)(shm+LDS_WS)+wid*64;
;   const bf16*ksrc=Kh+(long)lane*DM+wid*8;
;   const bf16*vsrc=Vh+(long)(16*(wid&3)+(lane>>2))*DM+(wid>>2)*32+(lane&3)*8;
;   const unsigned kdst=lds0+LDS_K+wid*1024, vdst=lds0+LDS_V+wid*1024;
;     ...
;   const int vb0=(int)(lds0+LDS_V)+((lane>>4)&1)*32+(lane&3)*8+(4*hi+((lane&15)>>2))*64;
;   const char*Kbase=shm+LDS_K; bf16x8 kf[8];
;   const lds_cptr shm3=(lds_cptr)shm; const lds_cptr kp0=shm3+LDS_K+hi*1024+r32*16; const lds_cptr vp0=shm3+LDS_V+((lane>>4)&1)*32+(lane&3)*8+(4*hi+((lane&15)>>2))*64;
;   const int NT=(q0+QB)/KVBLK;
;   DMA_K(0,0);DMA_V(0,0);DMA_K(1,SLOTB);
;   bf16x8 qr[4];
;   #pragma unroll
;   for(int d0=0;d0<4;++d0)qr[d0]=*reinterpret_cast<const bf16x8*>(&Qw[(long)r32*DM+d0*16+hi*8]);
;   float mhat=0.f,l_reg=0.f;f32x16 o[2];o[0]=f32x16{};o[1]=f32x16{};f32x16 negm=f32x16{};asm volatile("":"+v"(negm));
;   const int qrel=wid*QBLK+r32;
;   typedef float f32x4b __attribute__((ext_vector_type(4)));
;     ...
;   bool resc=false;
;     ...
;   f32x16 pA0,pA1,pB0,pB1;
;   int sl_prev=0,sl_cur=0,sl_next=SLOTB;
;     ...
;   DMA_K(2,2*SLOTB);
;   WAIT_BAR(3);
;   qkt(pA0,pA1,Kbase,qr,negm,r32,hi);asm volatile("s_nop 15\n\ts_nop 7":"+v"(pA0),"+v"(pA1));BIAS(pA0,pA1,0);CMASK(pA0,pA1,0);
.LBB0_400:
	s_or_b64 exec, exec, s[8:9]
	s_ashr_i32 s8, s40, 31
	s_lshr_b32 s8, s8, 29
	s_add_i32 s9, s40, s8
	s_ashr_i32 s8, s9, 3
	s_and_b32 s9, s9, 0x3fffff8
	s_sub_i32 s25, s40, s9
	s_ashr_i32 s9, s8, 31
	s_ashr_i32 s29, s24, 31
	s_lshl_b64 s[10:11], s[8:9], 11
	s_add_u32 s42, s24, s73
	s_addc_u32 s29, s29, 0
	s_add_u32 s44, s42, s10
	s_addc_u32 s45, s29, s11
	s_lshl_b64 s[10:11], s[44:45], 10
	s_add_u32 s29, s76, s10
	s_addc_u32 s46, s77, s11
	s_lshl_b32 s10, s25, 6
	s_ashr_i32 s11, s10, 31
	s_lshl_b64 s[42:43], s[10:11], 1
	s_add_u32 s10, s29, s42
	s_addc_u32 s11, s46, s43
	s_lshl_b64 s[8:9], s[8:9], 21
	s_add_u32 s25, s78, s8
	v_mov_b32_e32 v214, v212
	s_addc_u32 s29, s79, s9
	s_add_u32 s46, s25, s42
	v_ashrrev_i32_e32 v215, 31, v214
	s_addc_u32 s47, s29, s43
	s_waitcnt lgkmcnt(0)
	v_lshlrev_b64 v[2:3], 10, v[214:215]
	s_add_u32 s8, s80, s8
	v_lshl_add_u64 v[2:3], s[46:47], 0, v[2:3]
	v_ashrrev_i32_e32 v0, 2, v214
	s_addc_u32 s9, s81, s9
	v_lshl_add_u64 v[200:201], v[2:3], 0, s[26:27]
	v_add_u32_e32 v2, s84, v0
	s_add_u32 s8, s8, s42
	v_ashrrev_i32_e32 v3, 31, v2
	s_addc_u32 s9, s9, s43
	v_lshlrev_b64 v[2:3], 10, v[2:3]
	v_lshlrev_b32_e32 v215, 3, v214
	v_lshl_add_u64 v[2:3], s[8:9], 0, v[2:3]
	s_mov_b32 s29, s27
	v_and_b32_e32 v230, 24, v215
	v_lshl_add_u64 v[2:3], v[2:3], 0, s[28:29]
	v_lshlrev_b32_e32 v0, 1, v230
	s_mov_b32 s8, m0
	s_mov_b32 m0, s85
	s_nop 0
	global_load_lds_dwordx4 v[200:201], off
	s_mov_b32 m0, s8
	v_lshl_add_u64 v[34:35], v[2:3], 0, v[0:1]
	s_mov_b32 s8, m0
	s_mov_b32 m0, s86
	s_nop 0
	global_load_lds_dwordx4 v[34:35], off
	s_mov_b32 m0, s8
	s_cmp_lg_u32 0, -1
	s_cselect_b32 s8, 0, 0
	v_ashrrev_i32_e32 v229, 5, v214
	v_lshl_add_u64 v[2:3], v[200:201], 0, s[30:31]
	s_add_i32 s8, s8, s64
	s_add_i32 s9, s8, 0x2000
	s_mov_b32 s25, m0
	s_mov_b32 m0, s9
	s_nop 0
	global_load_lds_dwordx4 v[2:3], off
	s_mov_b32 m0, s25
	v_lshlrev_b32_e32 v2, 3, v229
	v_and_b32_e32 v228, 31, v214
	v_ashrrev_i32_e32 v3, 31, v2
	v_lshl_add_u64 v[2:3], v[2:3], 1, s[10:11]
	v_lshlrev_b32_e32 v0, 10, v228
	v_lshl_add_u64 v[10:11], v[2:3], 0, v[0:1]
	global_load_dwordx4 v[144:147], v[10:11], off
	global_load_dwordx4 v[136:139], v[10:11], off offset:32
	global_load_dwordx4 v[132:135], v[10:11], off offset:64
	global_load_dwordx4 v[128:131], v[10:11], off offset:96
	v_mov_b32_e32 v2, v1
	v_mov_b32_e32 v3, v1
	v_mov_b32_e32 v4, v1
	v_mov_b32_e32 v5, v1
	v_mov_b32_e32 v6, v1
	v_mov_b32_e32 v7, v1
	v_mov_b32_e32 v8, v1
	v_mov_b32_e32 v9, v1
	v_mov_b32_e32 v10, v1
	v_mov_b32_e32 v11, v1
	v_mov_b32_e32 v12, v1
	v_mov_b32_e32 v13, v1
	v_mov_b32_e32 v14, v1
	v_mov_b32_e32 v15, v1
	v_lshlrev_b32_e32 v0, 10, v229
	v_lshlrev_b32_e32 v16, 4, v228
	v_add3_u32 v235, 0, v0, v16
	v_mov_b32_e32 v0, v1
	v_mov_b64_e32 v[16:17], v[14:15]
	v_mov_b64_e32 v[14:15], v[12:13]
	v_mov_b64_e32 v[12:13], v[10:11]
	v_mov_b64_e32 v[10:11], v[8:9]
	v_mov_b64_e32 v[8:9], v[6:7]
	v_mov_b64_e32 v[6:7], v[4:5]
	v_mov_b64_e32 v[4:5], v[2:3]
	v_mov_b64_e32 v[2:3], v[0:1]
	v_lshl_add_u64 v[18:19], v[200:201], 0, s[34:35]
	s_addk_i32 s8, 0x4000
	s_mov_b32 s9, m0
	s_mov_b32 m0, s8
	s_nop 0
	global_load_lds_dwordx4 v[18:19], off
	s_mov_b32 m0, s9
	s_waitcnt vmcnt(3) lgkmcnt(0)
	s_barrier
	ds_read_b128 v[36:39], v235
	ds_read_b128 v[40:43], v235 offset:512
	v_mov_b32_e32 v0, v229
	s_waitcnt vmcnt(3) lgkmcnt(1)
	v_mfma_f32_32x32x16_bf16 v[18:33], v[36:39], v[144:147], v[2:17]
	s_waitcnt lgkmcnt(0)
	v_mfma_f32_32x32x16_bf16 v[2:17], v[40:43], v[144:147], v[2:17]
	ds_read_b128 v[36:39], v235 offset:2048
	ds_read_b128 v[40:43], v235 offset:2560
	s_waitcnt vmcnt(2) lgkmcnt(1)
	v_mfma_f32_32x32x16_bf16 v[18:33], v[36:39], v[136:139], v[18:33]
	s_waitcnt lgkmcnt(0)
	v_mfma_f32_32x32x16_bf16 v[2:17], v[40:43], v[136:139], v[2:17]
	ds_read_b128 v[36:39], v235 offset:4096
	ds_read_b128 v[40:43], v235 offset:4608
	s_waitcnt vmcnt(1) lgkmcnt(1)
	v_mfma_f32_32x32x16_bf16 v[18:33], v[36:39], v[132:135], v[18:33]
	s_waitcnt lgkmcnt(0)
	v_mfma_f32_32x32x16_bf16 v[2:17], v[40:43], v[132:135], v[2:17]
	ds_read_b128 v[36:39], v235 offset:6144
	ds_read_b128 v[40:43], v235 offset:6656
	s_waitcnt vmcnt(0) lgkmcnt(1)
	v_mfma_f32_32x32x16_bf16 v[18:33], v[36:39], v[128:131], v[18:33]
	s_waitcnt lgkmcnt(0)
	v_mfma_f32_32x32x16_bf16 v[2:17], v[40:43], v[128:131], v[2:17]
	s_nop 15
	s_nop 7
	s_nop 0
	v_lshl_add_u32 v0, v0, 4, 0
	v_add_u32_e32 v0, 0x14800, v0
	ds_read_b128 v[42:45], v0
	ds_read_b128 v[46:49], v0 offset:128
	ds_read_b128 v[50:53], v0 offset:32
	ds_read_b128 v[54:57], v0 offset:160
	ds_read_b128 v[58:61], v0 offset:64
	ds_read_b128 v[62:65], v0 offset:192
	ds_read_b128 v[66:69], v0 offset:96
	s_waitcnt lgkmcnt(6)
	v_add_f32_e32 v40, v20, v44
	v_add_f32_e32 v41, v21, v45
	s_waitcnt lgkmcnt(4)
	v_add_f32_e32 v38, v22, v50
	v_add_f32_e32 v39, v23, v51
	v_add_f32_e32 v36, v24, v52
	v_add_f32_e32 v37, v25, v53
	s_waitcnt lgkmcnt(2)
	v_add_f32_e32 v26, v26, v58
	v_add_f32_e32 v27, v27, v59
	v_add_f32_e32 v24, v28, v60
	v_add_f32_e32 v25, v29, v61
	s_waitcnt lgkmcnt(0)
	v_add_f32_e32 v22, v30, v66
	v_add_f32_e32 v23, v31, v67
	v_add_f32_e32 v20, v32, v68
	v_add_f32_e32 v21, v33, v69
	v_add_f32_e32 v18, v18, v42
	v_add_f32_e32 v19, v19, v43
	ds_read_b128 v[42:45], v0 offset:224
	v_add_f32_e32 v32, v4, v48
	v_add_f32_e32 v33, v5, v49
	v_add_f32_e32 v30, v6, v54
	v_add_f32_e32 v31, v7, v55
	v_add_f32_e32 v28, v8, v56
	v_add_f32_e32 v29, v9, v57
	v_add_f32_e32 v10, v10, v62
	v_add_f32_e32 v11, v11, v63
	v_add_f32_e32 v8, v12, v64
	v_add_f32_e32 v9, v13, v65
	s_waitcnt lgkmcnt(0)
	v_add_f32_e32 v6, v14, v42
	v_add_f32_e32 v7, v15, v43
	v_add_f32_e32 v4, v16, v44
	v_add_f32_e32 v5, v17, v45
	v_add_f32_e32 v2, v2, v46
	v_add_f32_e32 v3, v3, v47
	s_ashr_i32 s29, s95, 6
	s_cmp_lt_i32 s29, 5
	v_or_b32_e32 v233, s73, v228
	s_cbranch_scc0 .LBB0_402
; __device__ __forceinline__ void cmask(f32x16&p0,f32x16&p1,int jb,int qrel,int hi){
;   const float NEG=-INFINITY; int kb=64*jb+4*hi;
;   #pragma unroll
;   for(int r=0;r<16;++r){int kv=kb+(r&3)+8*(r>>2); if(kv>qrel)p0[r]=NEG; if(kv+32>qrel)p1[r]=NEG;}
; }
	v_mov_b32_e32 v0, v233
	v_mov_b32_e32 v12, v229
	s_nop 0
	v_lshlrev_b32_e32 v12, 2, v12
	v_subrev_u32_e32 v12, s24, v12
	v_add_u32_e32 v13, 32, v12
	v_cmp_le_i32_e32 vcc, v13, v0
	v_add_u32_e32 v13, 33, v12
	s_nop 0
	v_cndmask_b32_e32 v2, v227, v2, vcc
	v_cmp_lt_i32_e32 vcc, v12, v0
	s_nop 1
	v_cndmask_b32_e32 v19, v227, v19, vcc
	v_cmp_le_i32_e32 vcc, v12, v0
	s_nop 1
	v_cndmask_b32_e32 v18, v227, v18, vcc
	v_cmp_le_i32_e32 vcc, v13, v0
	v_or_b32_e32 v13, 2, v12
	s_nop 0
	v_cndmask_b32_e32 v3, v227, v3, vcc
	v_cmp_le_i32_e32 vcc, v13, v0
	v_add_u32_e32 v13, 34, v12
	s_nop 0
	v_cndmask_b32_e32 v40, v227, v40, vcc
	v_cmp_le_i32_e32 vcc, v13, v0
	v_or_b32_e32 v13, 3, v12
	s_nop 0
	v_cndmask_b32_e32 v32, v227, v32, vcc
	v_cmp_le_i32_e32 vcc, v13, v0
	v_add_u32_e32 v13, 35, v12
	s_nop 0
	v_cndmask_b32_e32 v41, v227, v41, vcc
	v_cmp_le_i32_e32 vcc, v13, v0
	v_add_u32_e32 v13, 8, v12
	s_nop 0
	v_cndmask_b32_e32 v33, v227, v33, vcc
	v_cmp_le_i32_e32 vcc, v13, v0
	v_add_u32_e32 v13, 40, v12
	s_nop 0
	v_cndmask_b32_e32 v38, v227, v38, vcc
	v_cmp_le_i32_e32 vcc, v13, v0
	v_add_u32_e32 v13, 9, v12
	s_nop 0
	v_cndmask_b32_e32 v30, v227, v30, vcc
	v_cmp_le_i32_e32 vcc, v13, v0
	v_add_u32_e32 v13, 41, v12
	s_nop 0
	v_cndmask_b32_e32 v39, v227, v39, vcc
	v_cmp_le_i32_e32 vcc, v13, v0
	v_add_u32_e32 v13, 10, v12
	s_nop 0
	v_cndmask_b32_e32 v31, v227, v31, vcc
	v_cmp_le_i32_e32 vcc, v13, v0
	v_add_u32_e32 v13, 42, v12
	s_nop 0
	v_cndmask_b32_e32 v36, v227, v36, vcc
	v_cmp_le_i32_e32 vcc, v13, v0
	v_add_u32_e32 v13, 11, v12
	s_nop 0
	v_cndmask_b32_e32 v28, v227, v28, vcc
	v_cmp_le_i32_e32 vcc, v13, v0
	v_add_u32_e32 v13, 43, v12
	s_nop 0
	v_cndmask_b32_e32 v37, v227, v37, vcc
	v_cmp_le_i32_e32 vcc, v13, v0
	v_add_u32_e32 v13, 16, v12
	s_nop 0
	v_cndmask_b32_e32 v29, v227, v29, vcc
	v_cmp_le_i32_e32 vcc, v13, v0
	v_add_u32_e32 v13, 48, v12
	s_nop 0
	v_cndmask_b32_e32 v26, v227, v26, vcc
	v_cmp_le_i32_e32 vcc, v13, v0
	v_add_u32_e32 v13, 17, v12
	s_nop 0
	v_cndmask_b32_e32 v10, v227, v10, vcc
	v_cmp_le_i32_e32 vcc, v13, v0
	v_add_u32_e32 v13, 49, v12
	s_nop 0
	v_cndmask_b32_e32 v27, v227, v27, vcc
	v_cmp_le_i32_e32 vcc, v13, v0
	v_add_u32_e32 v13, 18, v12
	s_nop 0
	v_cndmask_b32_e32 v11, v227, v11, vcc
	v_cmp_le_i32_e32 vcc, v13, v0
	v_add_u32_e32 v13, 50, v12
	s_nop 0
	v_cndmask_b32_e32 v24, v227, v24, vcc
	v_cmp_le_i32_e32 vcc, v13, v0
	v_add_u32_e32 v13, 19, v12
	s_nop 0
	v_cndmask_b32_e32 v8, v227, v8, vcc
	v_cmp_le_i32_e32 vcc, v13, v0
	v_add_u32_e32 v13, 51, v12
	s_nop 0
	v_cndmask_b32_e32 v25, v227, v25, vcc
	v_cmp_le_i32_e32 vcc, v13, v0
	v_add_u32_e32 v13, 24, v12
	s_nop 0
	v_cndmask_b32_e32 v9, v227, v9, vcc
	v_cmp_le_i32_e32 vcc, v13, v0
	v_add_u32_e32 v13, 56, v12
	s_nop 0
	v_cndmask_b32_e32 v22, v227, v22, vcc
	v_cmp_le_i32_e32 vcc, v13, v0
	v_add_u32_e32 v13, 25, v12
	s_nop 0
	v_cndmask_b32_e32 v6, v227, v6, vcc
	v_cmp_le_i32_e32 vcc, v13, v0
	v_add_u32_e32 v13, 57, v12
	s_nop 0
	v_cndmask_b32_e32 v23, v227, v23, vcc
	v_cmp_le_i32_e32 vcc, v13, v0
	v_add_u32_e32 v13, 26, v12
	s_nop 0
	v_cndmask_b32_e32 v7, v227, v7, vcc
	v_cmp_le_i32_e32 vcc, v13, v0
	v_add_u32_e32 v13, 58, v12
	s_nop 0
	v_cndmask_b32_e32 v20, v227, v20, vcc
	v_cmp_le_i32_e32 vcc, v13, v0
	v_add_u32_e32 v13, 27, v12
	v_add_u32_e32 v12, 59, v12
	v_cndmask_b32_e32 v4, v227, v4, vcc
	v_cmp_le_i32_e32 vcc, v13, v0
	s_nop 1
	v_cndmask_b32_e32 v21, v227, v21, vcc
	v_cmp_le_i32_e32 vcc, v12, v0
	s_nop 1
	v_cndmask_b32_e32 v5, v227, v5, vcc

.LBB0_404:
	v_add_u32_e32 v0, s24, v236
	ds_read_b64_tr_b16 v[192:193], v0 offset:24576
	ds_read_b64_tr_b16 v[194:195], v0 offset:25088
	v_add_f32_e32 v2, v80, v81
	v_add_f32_e32 v2, v82, v2
	v_add_f32_e32 v2, v83, v2
	v_add_f32_e32 v2, v84, v2
	v_add_f32_e32 v2, v85, v2
	v_cvt_pk_bf16_f32 v156, v80, v81
	v_cvt_pk_bf16_f32 v157, v82, v83
	s_waitcnt lgkmcnt(9)
	v_mfma_f32_32x32x16_bf16 v[96:111], v[188:191], v[144:147], v[48:63]
	ds_read_b64_tr_b16 v[188:189], v0 offset:28672
	ds_read_b64_tr_b16 v[190:191], v0 offset:29184
	v_add_f32_e32 v2, v86, v2
	v_add_f32_e32 v2, v87, v2
	v_add_f32_e32 v2, v88, v2
	v_add_f32_e32 v2, v89, v2
	v_cvt_pk_bf16_f32 v158, v84, v85
	v_cvt_pk_bf16_f32 v159, v86, v87
	s_waitcnt lgkmcnt(10)
	v_mfma_f32_32x32x16_bf16 v[112:127], v[184:187], v[144:147], v[48:63]
	ds_read_b64_tr_b16 v[184:185], v0 offset:25600
	ds_read_b64_tr_b16 v[186:187], v0 offset:26112
	v_add_f32_e32 v2, v90, v2
	v_add_f32_e32 v2, v91, v2
	v_add_f32_e32 v2, v92, v2
	v_add_f32_e32 v2, v93, v2
	v_cvt_pk_bf16_f32 v152, v88, v89
	v_cvt_pk_bf16_f32 v153, v90, v91
	s_waitcnt lgkmcnt(11)
	v_mfma_f32_32x32x16_bf16 v[96:111], v[180:183], v[136:139], v[96:111]
	ds_read_b64_tr_b16 v[180:181], v0 offset:29696
	ds_read_b64_tr_b16 v[182:183], v0 offset:30208
	v_add_f32_e32 v2, v94, v2
	v_add_f32_e32 v2, v95, v2
	v_add_f32_e32 v2, v64, v2
	v_add_f32_e32 v2, v65, v2
	v_cvt_pk_bf16_f32 v154, v92, v93
	v_cvt_pk_bf16_f32 v155, v94, v95
	s_waitcnt lgkmcnt(12)
	v_mfma_f32_32x32x16_bf16 v[112:127], v[176:179], v[136:139], v[112:127]
	ds_read_b64_tr_b16 v[176:177], v0 offset:26624
	ds_read_b64_tr_b16 v[178:179], v0 offset:27136
	v_add_f32_e32 v2, v66, v2
	v_add_f32_e32 v2, v67, v2
	v_add_f32_e32 v2, v68, v2
	v_add_f32_e32 v2, v69, v2
	v_cvt_pk_bf16_f32 v148, v64, v65
	v_cvt_pk_bf16_f32 v149, v66, v67
	s_waitcnt lgkmcnt(13)
	v_mfma_f32_32x32x16_bf16 v[96:111], v[172:175], v[132:135], v[96:111]
	ds_read_b64_tr_b16 v[10:11], v0 offset:30720
	ds_read_b64_tr_b16 v[12:13], v0 offset:31232
	v_add_f32_e32 v2, v70, v2
	v_add_f32_e32 v2, v71, v2
	v_add_f32_e32 v2, v72, v2
	v_add_f32_e32 v2, v73, v2
	v_cvt_pk_bf16_f32 v150, v68, v69
	v_cvt_pk_bf16_f32 v151, v70, v71
	s_waitcnt lgkmcnt(14)
	v_mfma_f32_32x32x16_bf16 v[112:127], v[168:171], v[132:135], v[112:127]
	ds_read_b64_tr_b16 v[6:7], v0 offset:27648
	ds_read_b64_tr_b16 v[8:9], v0 offset:28160
	v_add_f32_e32 v2, v74, v2
	v_add_f32_e32 v2, v75, v2
	v_add_f32_e32 v2, v76, v2
	v_add_f32_e32 v14, v77, v2
	v_cvt_pk_bf16_f32 v140, v72, v73
	v_cvt_pk_bf16_f32 v141, v74, v75
	s_waitcnt lgkmcnt(14)
	v_mfma_f32_32x32x16_bf16 v[96:111], v[164:167], v[128:131], v[96:111]
	ds_read_b64_tr_b16 v[2:3], v0 offset:31744
	ds_read_b64_tr_b16 v[4:5], v0 offset:32256
	v_add_f32_e32 v0, v78, v14
	v_add_f32_e32 v0, v79, v0
	v_add_f32_e32 v0, 0, v0
	v_cvt_pk_bf16_f32 v142, v76, v77
	v_cvt_pk_bf16_f32 v143, v78, v79
	v_mfma_f32_32x32x16_bf16 v[112:127], v[160:163], v[128:131], v[112:127]
	v_lshl_add_u64 v[14:15], v[206:207], 0, s[38:39]
	s_add_i32 s24, s52, s85
	s_mov_b32 s25, m0
	s_mov_b32 m0, s24
	s_nop 0
	global_load_lds_dwordx4 v[14:15], off
	s_mov_b32 m0, s25
	v_lshl_add_u64 v[14:15], v[204:205], 0, s[38:39]
	s_add_i32 s24, s50, s86
	s_mov_b32 s25, m0
	s_mov_b32 m0, s24
	s_nop 0
	global_load_lds_dwordx4 v[14:15], off
	s_mov_b32 m0, s25
	v_mov_b32_e32 v14, v229
	s_nop 0
	v_lshl_add_u32 v80, v14, 4, s51
	ds_read_b128 v[160:163], v80
	ds_read_b128 v[164:167], v80 offset:128
	ds_read_b128 v[168:171], v80 offset:32
	ds_read_b128 v[172:175], v80 offset:160
	ds_read_b128 v[196:199], v80 offset:64
	ds_read_b128 v[240:243], v80 offset:192
	ds_read_b128 v[244:247], v80 offset:96
	ds_read_b128 v[252:255], v80 offset:224
	s_waitcnt lgkmcnt(7)
	v_add_f32_e32 v64, v96, v160
	v_add_f32_e32 v65, v97, v161
	v_add_f32_e32 v82, v98, v162
	v_add_f32_e32 v83, v99, v163
	s_waitcnt lgkmcnt(6)
	v_add_f32_e32 v14, v112, v164
	v_add_f32_e32 v15, v113, v165
	v_add_f32_e32 v66, v114, v166
	v_add_f32_e32 v67, v115, v167
	s_waitcnt lgkmcnt(5)
	v_add_f32_e32 v84, v100, v168
	v_add_f32_e32 v85, v101, v169
	v_add_f32_e32 v86, v102, v170
	v_add_f32_e32 v87, v103, v171
	s_waitcnt lgkmcnt(4)
	v_add_f32_e32 v68, v116, v172
	v_add_f32_e32 v69, v117, v173
	v_add_f32_e32 v70, v118, v174
	v_add_f32_e32 v71, v119, v175
	s_waitcnt lgkmcnt(3)
	v_add_f32_e32 v88, v104, v196
	v_add_f32_e32 v89, v105, v197
	v_add_f32_e32 v90, v106, v198
	v_add_f32_e32 v91, v107, v199
	s_waitcnt lgkmcnt(2)
	v_add_f32_e32 v72, v120, v240
	v_add_f32_e32 v73, v121, v241
	v_add_f32_e32 v74, v122, v242
	v_add_f32_e32 v75, v123, v243
	s_waitcnt lgkmcnt(1)
	v_add_f32_e32 v92, v108, v244
	v_add_f32_e32 v93, v109, v245
	v_add_f32_e32 v94, v110, v246
	v_add_f32_e32 v95, v111, v247
	s_waitcnt lgkmcnt(0)
	v_add_f32_e32 v76, v124, v252
	v_add_f32_e32 v77, v125, v253
	v_add_f32_e32 v78, v126, v254
	v_add_f32_e32 v79, v127, v255
	v_max_f32_e32 v80, v64, v65
	v_max3_f32 v81, v82, v83, v15
	v_max3_f32 v80, v80, v14, v66
	v_max3_f32 v80, v80, v67, v84
	v_max3_f32 v81, v81, v86, v87
	v_max3_f32 v80, v80, v85, v68
	v_max3_f32 v81, v81, v70, v71
	v_max3_f32 v80, v80, v69, v88
	v_max3_f32 v81, v81, v90, v91
	v_max3_f32 v80, v80, v89, v72
	v_max3_f32 v81, v81, v74, v75
	v_max3_f32 v80, v80, v73, v92
	v_max3_f32 v81, v81, v94, v95
	v_max3_f32 v80, v80, v93, v76
	v_max3_f32 v81, v81, v78, v79
	v_add_f32_e32 v209, v238, v0
	v_max3_f32 v0, v80, v77, v81
	v_mov_b32_e32 v80, v0
	s_nop 1
	v_permlane32_swap_b32_e32 v0, v80
	v_max_f32_e32 v80, v80, v80
	v_max_f32_e32 v0, v0, v0
	v_max_f32_e32 v0, v0, v80
	v_cmp_lt_f32_e32 vcc, s92, v0
	s_cmp_lg_u64 vcc, 0
	s_cselect_b64 s[46:47], -1, 0
	s_cbranch_vccnz .LBB0_412

.LBB0_407:
	s_add_i32 s24, s50, 0x2000
	s_cmpk_lg_i32 s50, 0x4000
	s_cselect_b32 s96, s24, 0
	v_add_u32_e32 v4, s52, v236
	ds_read_b64_tr_b16 v[176:177], v4 offset:24576
	ds_read_b64_tr_b16 v[178:179], v4 offset:25088
	v_add_f32_e32 v2, v80, v81
	v_add_f32_e32 v2, v82, v2
	v_add_f32_e32 v2, v83, v2
	v_add_f32_e32 v2, v84, v2
	v_add_f32_e32 v2, v85, v2
	v_cvt_pk_bf16_f32 v156, v80, v81
	v_cvt_pk_bf16_f32 v157, v82, v83
	s_waitcnt lgkmcnt(9)
	v_mfma_f32_32x32x16_bf16 v[96:111], v[112:115], v[144:147], v[48:63]
	ds_read_b64_tr_b16 v[172:173], v4 offset:28672
	ds_read_b64_tr_b16 v[174:175], v4 offset:29184
	v_add_f32_e32 v2, v86, v2
	v_add_f32_e32 v2, v87, v2
	v_add_f32_e32 v2, v88, v2
	v_add_f32_e32 v2, v89, v2
	v_cvt_pk_bf16_f32 v158, v84, v85
	v_cvt_pk_bf16_f32 v159, v86, v87
	s_waitcnt lgkmcnt(10)
	v_mfma_f32_32x32x16_bf16 v[112:127], v[164:167], v[144:147], v[48:63]
	ds_read_b64_tr_b16 v[168:169], v4 offset:25600
	ds_read_b64_tr_b16 v[170:171], v4 offset:26112
	v_add_f32_e32 v2, v90, v2
	v_add_f32_e32 v2, v91, v2
	v_add_f32_e32 v2, v92, v2
	v_add_f32_e32 v2, v93, v2
	v_cvt_pk_bf16_f32 v152, v88, v89
	v_cvt_pk_bf16_f32 v153, v90, v91
	s_waitcnt lgkmcnt(11)
	v_mfma_f32_32x32x16_bf16 v[96:111], v[196:199], v[136:139], v[96:111]
	ds_read_b64_tr_b16 v[164:165], v4 offset:29696
	ds_read_b64_tr_b16 v[166:167], v4 offset:30208
	v_add_f32_e32 v2, v94, v2
	v_add_f32_e32 v2, v95, v2
	v_add_f32_e32 v2, v64, v2
	v_add_f32_e32 v2, v65, v2
	v_cvt_pk_bf16_f32 v154, v92, v93
	v_cvt_pk_bf16_f32 v155, v94, v95
	s_waitcnt lgkmcnt(12)
	v_mfma_f32_32x32x16_bf16 v[112:127], v[160:163], v[136:139], v[112:127]
	ds_read_b64_tr_b16 v[160:161], v4 offset:26624
	ds_read_b64_tr_b16 v[162:163], v4 offset:27136
	v_add_f32_e32 v2, v66, v2
	v_add_f32_e32 v2, v67, v2
	v_add_f32_e32 v2, v68, v2
	v_add_f32_e32 v2, v69, v2
	v_cvt_pk_bf16_f32 v148, v64, v65
	v_cvt_pk_bf16_f32 v149, v66, v67
	s_waitcnt lgkmcnt(13)
	v_mfma_f32_32x32x16_bf16 v[96:111], v[192:195], v[132:135], v[96:111]
	ds_read_b64_tr_b16 v[10:11], v4 offset:30720
	ds_read_b64_tr_b16 v[12:13], v4 offset:31232
	v_add_f32_e32 v2, v70, v2
	v_add_f32_e32 v2, v71, v2
	v_add_f32_e32 v2, v72, v2
	v_add_f32_e32 v2, v73, v2
	v_cvt_pk_bf16_f32 v150, v68, v69
	v_cvt_pk_bf16_f32 v151, v70, v71
	s_waitcnt lgkmcnt(14)
	v_mfma_f32_32x32x16_bf16 v[112:127], v[184:187], v[132:135], v[112:127]
	ds_read_b64_tr_b16 v[6:7], v4 offset:27648
	ds_read_b64_tr_b16 v[8:9], v4 offset:28160
	v_add_f32_e32 v2, v74, v2
	v_add_f32_e32 v2, v75, v2
	v_add_f32_e32 v2, v76, v2
	v_add_f32_e32 v14, v77, v2
	v_cvt_pk_bf16_f32 v140, v72, v73
	v_cvt_pk_bf16_f32 v141, v74, v75
	s_waitcnt lgkmcnt(14)
	v_mfma_f32_32x32x16_bf16 v[96:111], v[188:191], v[128:131], v[96:111]
	ds_read_b64_tr_b16 v[2:3], v4 offset:31744
	ds_read_b64_tr_b16 v[4:5], v4 offset:32256
	v_add_f32_e32 v14, v78, v14
	v_add_f32_e32 v14, v79, v14
	v_add_f32_e32 v80, 0, v14
	v_cvt_pk_bf16_f32 v142, v76, v77
	v_cvt_pk_bf16_f32 v143, v78, v79
	v_mfma_f32_32x32x16_bf16 v[112:127], v[180:183], v[128:131], v[112:127]
	s_add_i32 s24, s50, s85
	s_mov_b32 s25, m0
	s_mov_b32 m0, s24
	s_nop 0
	global_load_lds_dwordx4 v[206:207], off
	s_mov_b32 m0, s25
	v_mov_b32_e32 v14, v229
	s_add_i32 s24, s96, s86
	s_mov_b32 s25, m0
	s_mov_b32 m0, s24
	s_nop 0
	global_load_lds_dwordx4 v[204:205], off
	s_mov_b32 m0, s25
	s_nop 0
	v_lshl_add_u32 v81, v14, 4, s51
	ds_read_b128 v[180:183], v81 offset:256
	ds_read_b128 v[184:187], v81 offset:384
	ds_read_b128 v[188:191], v81 offset:288
	ds_read_b128 v[192:195], v81 offset:416
	ds_read_b128 v[196:199], v81 offset:320
	ds_read_b128 v[240:243], v81 offset:448
	ds_read_b128 v[244:247], v81 offset:352
	ds_read_b128 v[252:255], v81 offset:480
	s_waitcnt lgkmcnt(7)
	v_add_f32_e32 v64, v96, v180
	v_add_f32_e32 v65, v97, v181
	v_add_f32_e32 v82, v98, v182
	v_add_f32_e32 v83, v99, v183
	s_waitcnt lgkmcnt(6)
	v_add_f32_e32 v14, v112, v184
	v_add_f32_e32 v15, v113, v185
	v_add_f32_e32 v66, v114, v186
	v_add_f32_e32 v67, v115, v187
	s_waitcnt lgkmcnt(5)
	v_add_f32_e32 v84, v100, v188
	v_add_f32_e32 v85, v101, v189
	v_add_f32_e32 v86, v102, v190
	v_add_f32_e32 v87, v103, v191
	s_waitcnt lgkmcnt(4)
	v_add_f32_e32 v68, v116, v192
	v_add_f32_e32 v69, v117, v193
	v_add_f32_e32 v70, v118, v194
	v_add_f32_e32 v71, v119, v195
	s_waitcnt lgkmcnt(3)
	v_add_f32_e32 v88, v104, v196
	v_add_f32_e32 v89, v105, v197
	v_add_f32_e32 v90, v106, v198
	v_add_f32_e32 v91, v107, v199
	s_waitcnt lgkmcnt(2)
	v_add_f32_e32 v72, v120, v240
	v_add_f32_e32 v73, v121, v241
	v_add_f32_e32 v74, v122, v242
	v_add_f32_e32 v75, v123, v243
	s_waitcnt lgkmcnt(1)
	v_add_f32_e32 v92, v108, v244
	v_add_f32_e32 v93, v109, v245
	v_add_f32_e32 v94, v110, v246
	v_add_f32_e32 v95, v111, v247
	s_waitcnt lgkmcnt(0)
	v_add_f32_e32 v76, v124, v252
	v_add_f32_e32 v77, v125, v253
	v_add_f32_e32 v78, v126, v254
	v_add_f32_e32 v79, v127, v255
	v_max_f32_e32 v81, v64, v65
	v_max3_f32 v96, v82, v83, v15
	v_max3_f32 v81, v81, v14, v66
	v_max3_f32 v81, v81, v67, v84
	v_max3_f32 v96, v96, v86, v87
	v_max3_f32 v81, v81, v85, v68
	v_max3_f32 v96, v96, v70, v71
	v_max3_f32 v81, v81, v69, v88
	v_max3_f32 v96, v96, v90, v91
	v_max3_f32 v81, v81, v89, v72
	v_max3_f32 v96, v96, v74, v75
	v_max3_f32 v81, v81, v73, v92
	v_max3_f32 v96, v96, v94, v95
	v_max3_f32 v81, v81, v93, v76
	v_max3_f32 v96, v96, v78, v79
	v_add_f32_e32 v238, v209, v80
	v_max3_f32 v80, v81, v77, v96
	v_mov_b32_e32 v81, v80
	s_nop 1
	v_permlane32_swap_b32_e32 v80, v81
	v_max_f32_e32 v81, v81, v81
	v_max_f32_e32 v80, v80, v80
	v_max_f32_e32 v80, v80, v81
	v_cmp_lt_f32_e32 vcc, s92, v80
	s_cmp_lg_u64 vcc, 0
	s_cselect_b64 s[46:47], -1, 0
	s_cbranch_vccnz .LBB0_415

; __device__ __forceinline__ void cmask(f32x16&p0,f32x16&p1,int jb,int qrel,int hi){
;   const float NEG=-INFINITY; int kb=64*jb+4*hi;
;   #pragma unroll
;   for(int r=0;r<16;++r){int kv=kb+(r&3)+8*(r>>2); if(kv>qrel)p0[r]=NEG; if(kv+32>qrel)p1[r]=NEG;}
; }
.LBB0_423:
	v_mov_b32_e32 v64, v229
	s_add_i32 s10, s97, s86
	s_mov_b32 s11, m0
	s_mov_b32 m0, s10
	s_nop 0
	global_load_lds_dwordx4 v[14:15], off
	s_mov_b32 m0, s11
	s_nop 0
	v_lshl_add_u32 v165, v64, 4, s65
	ds_read_b128 v[64:67], v165
	ds_read_b128 v[68:71], v165 offset:128
	ds_read_b128 v[72:75], v165 offset:32
	ds_read_b128 v[76:79], v165 offset:160
	ds_read_b128 v[88:91], v165 offset:64
	ds_read_b128 v[160:163], v165 offset:192
	ds_read_b128 v[92:95], v165 offset:96
	s_waitcnt lgkmcnt(6)
	v_add_f32_e32 v82, v114, v66
	v_add_f32_e32 v83, v115, v67
	s_waitcnt lgkmcnt(4)
	v_add_f32_e32 v86, v118, v74
	v_add_f32_e32 v87, v119, v75
	s_waitcnt lgkmcnt(2)
	v_add_f32_e32 v90, v122, v90
	v_add_f32_e32 v91, v123, v91
	v_add_f32_e32 v80, v112, v64
	v_add_f32_e32 v81, v113, v65
	s_waitcnt lgkmcnt(0)
	v_add_f32_e32 v94, v126, v94
	v_add_f32_e32 v95, v127, v95
	v_add_f32_e32 v84, v116, v72
	v_add_f32_e32 v85, v117, v73
	v_add_f32_e32 v88, v120, v88
	v_add_f32_e32 v89, v121, v89
	v_add_f32_e32 v92, v124, v92
	v_add_f32_e32 v93, v125, v93
	ds_read_b128 v[112:115], v165 offset:224
	v_add_f32_e32 v66, v98, v70
	v_add_f32_e32 v67, v99, v71
	v_add_f32_e32 v70, v102, v78
	v_add_f32_e32 v71, v103, v79
	v_add_f32_e32 v74, v106, v162
	v_add_f32_e32 v75, v107, v163
	v_add_f32_e32 v64, v96, v68
	v_add_f32_e32 v65, v97, v69
	s_waitcnt lgkmcnt(0)
	v_add_f32_e32 v78, v110, v114
	v_add_f32_e32 v79, v111, v115
	v_add_f32_e32 v68, v100, v76
	v_add_f32_e32 v69, v101, v77
	v_add_f32_e32 v72, v104, v160
	v_add_f32_e32 v73, v105, v161
	v_add_f32_e32 v76, v108, v112
	v_add_f32_e32 v77, v109, v113
	s_add_i32 s53, s58, s52
	s_add_i32 s10, s53, 2
	s_cmp_lt_i32 s10, 0
	s_cbranch_scc1 .LBB0_425
	v_mov_b32_e32 v96, v233
	v_mov_b32_e32 v97, v229
	s_nop 0
	v_lshl_add_u32 v97, v97, 2, s55
	v_add_u32_e32 v99, 0xffffffa5, v97
	v_add_u32_e32 v98, 0xffffff85, v97
	v_cmp_le_i32_e32 vcc, v99, v96
	s_nop 1
	v_cndmask_b32_e32 v64, v227, v64, vcc
	v_cmp_lt_i32_e32 vcc, v98, v96
	s_nop 1
	v_cndmask_b32_e32 v81, v227, v81, vcc
	v_cmp_le_i32_e32 vcc, v98, v96
	v_add_u32_e32 v98, 0xffffffa6, v97
	s_nop 0
	v_cndmask_b32_e32 v80, v227, v80, vcc
	v_cmp_le_i32_e32 vcc, v98, v96
	v_add_u32_e32 v98, 0xffffff87, v97
	s_nop 0
	v_cndmask_b32_e32 v65, v227, v65, vcc
	v_cmp_le_i32_e32 vcc, v98, v96
	v_add_u32_e32 v98, 0xffffffa7, v97
	s_nop 0
	v_cndmask_b32_e32 v82, v227, v82, vcc
	v_cmp_le_i32_e32 vcc, v98, v96
	v_add_u32_e32 v98, 0xffffff88, v97
	s_nop 0
	v_cndmask_b32_e32 v66, v227, v66, vcc
	v_cmp_le_i32_e32 vcc, v98, v96
	v_add_u32_e32 v98, 0xffffffa8, v97
	s_nop 0
	v_cndmask_b32_e32 v83, v227, v83, vcc
	v_cmp_le_i32_e32 vcc, v98, v96
	v_add_u32_e32 v98, 0xffffff8d, v97
	s_nop 0
	v_cndmask_b32_e32 v67, v227, v67, vcc
	v_cmp_le_i32_e32 vcc, v98, v96
	v_add_u32_e32 v98, 0xffffffad, v97
	s_nop 0
	v_cndmask_b32_e32 v84, v227, v84, vcc
	v_cmp_le_i32_e32 vcc, v98, v96
	v_add_u32_e32 v98, 0xffffff8e, v97
	s_nop 0
	v_cndmask_b32_e32 v68, v227, v68, vcc
	v_cmp_le_i32_e32 vcc, v98, v96
	v_add_u32_e32 v98, 0xffffffae, v97
	s_nop 0
	v_cndmask_b32_e32 v85, v227, v85, vcc
	v_cmp_le_i32_e32 vcc, v98, v96
	v_add_u32_e32 v98, 0xffffff8f, v97
	s_nop 0
	v_cndmask_b32_e32 v69, v227, v69, vcc
	v_cmp_le_i32_e32 vcc, v98, v96
	v_add_u32_e32 v98, 0xffffffaf, v97
	s_nop 0
	v_cndmask_b32_e32 v86, v227, v86, vcc
	v_cmp_le_i32_e32 vcc, v98, v96
	v_add_u32_e32 v98, 0xffffff90, v97
	s_nop 0
	v_cndmask_b32_e32 v70, v227, v70, vcc
	v_cmp_le_i32_e32 vcc, v98, v96
	v_add_u32_e32 v98, 0xffffffb0, v97
	s_nop 0
	v_cndmask_b32_e32 v87, v227, v87, vcc
	v_cmp_le_i32_e32 vcc, v98, v96
	v_add_u32_e32 v98, 0xffffff95, v97
	s_nop 0
	v_cndmask_b32_e32 v71, v227, v71, vcc
	v_cmp_le_i32_e32 vcc, v98, v96
	v_add_u32_e32 v98, 0xffffffb5, v97
	s_nop 0
	v_cndmask_b32_e32 v88, v227, v88, vcc
	v_cmp_le_i32_e32 vcc, v98, v96
	v_add_u32_e32 v98, 0xffffff96, v97
	s_nop 0
	v_cndmask_b32_e32 v72, v227, v72, vcc
	v_cmp_le_i32_e32 vcc, v98, v96
	v_add_u32_e32 v98, 0xffffffb6, v97
	s_nop 0
	v_cndmask_b32_e32 v89, v227, v89, vcc
	v_cmp_le_i32_e32 vcc, v98, v96
	v_add_u32_e32 v98, 0xffffff97, v97
	s_nop 0
	v_cndmask_b32_e32 v73, v227, v73, vcc
	v_cmp_le_i32_e32 vcc, v98, v96
	v_add_u32_e32 v98, 0xffffffb7, v97
	s_nop 0
	v_cndmask_b32_e32 v90, v227, v90, vcc
	v_cmp_le_i32_e32 vcc, v98, v96
	v_add_u32_e32 v98, 0xffffff98, v97
	s_nop 0
	v_cndmask_b32_e32 v74, v227, v74, vcc
	v_cmp_le_i32_e32 vcc, v98, v96
	v_add_u32_e32 v98, 0xffffffb8, v97
	s_nop 0
	v_cndmask_b32_e32 v91, v227, v91, vcc
	v_cmp_le_i32_e32 vcc, v98, v96
	v_add_u32_e32 v98, 0xffffff9d, v97
	s_nop 0
	v_cndmask_b32_e32 v75, v227, v75, vcc
	v_cmp_le_i32_e32 vcc, v98, v96
	v_add_u32_e32 v98, 0xffffffbd, v97
	s_nop 0
	v_cndmask_b32_e32 v92, v227, v92, vcc
	v_cmp_le_i32_e32 vcc, v98, v96
	v_add_u32_e32 v98, 0xffffff9e, v97
	s_nop 0
	v_cndmask_b32_e32 v76, v227, v76, vcc
	v_cmp_le_i32_e32 vcc, v98, v96
	v_add_u32_e32 v98, 0xffffffbe, v97
	s_nop 0
	v_cndmask_b32_e32 v93, v227, v93, vcc
	v_cmp_le_i32_e32 vcc, v98, v96
	v_add_u32_e32 v98, 0xffffff9f, v97
	s_nop 0
	v_cndmask_b32_e32 v77, v227, v77, vcc
	v_cmp_le_i32_e32 vcc, v98, v96
	v_add_u32_e32 v98, 0xffffffbf, v97
	s_nop 0
	v_cndmask_b32_e32 v94, v227, v94, vcc
	v_cmp_le_i32_e32 vcc, v98, v96
	v_add_u32_e32 v98, 0xffffffa0, v97
	v_subrev_u32_e32 v97, 64, v97
	v_cndmask_b32_e32 v78, v227, v78, vcc
	v_cmp_le_i32_e32 vcc, v98, v96
	s_nop 1
	v_cndmask_b32_e32 v95, v227, v95, vcc
	v_cmp_le_i32_e32 vcc, v97, v96
	s_nop 1
	v_cndmask_b32_e32 v79, v227, v79, vcc

; __device__ __forceinline__ void cmask(f32x16&p0,f32x16&p1,int jb,int qrel,int hi){
;   const float NEG=-INFINITY; int kb=64*jb+4*hi;
;   #pragma unroll
;   for(int r=0;r<16;++r){int kv=kb+(r&3)+8*(r>>2); if(kv>qrel)p0[r]=NEG; if(kv+32>qrel)p1[r]=NEG;}
; }
.LBB0_434:
	v_mov_b32_e32 v64, v229
	s_nop 0
	v_lshl_add_u32 v241, v64, 4, s65
	ds_read_b128 v[64:67], v241 offset:256
	ds_read_b128 v[68:71], v241 offset:384
	ds_read_b128 v[72:75], v241 offset:288
	ds_read_b128 v[76:79], v241 offset:416
	ds_read_b128 v[88:91], v241 offset:320
	ds_read_b128 v[242:245], v241 offset:448
	ds_read_b128 v[92:95], v241 offset:352
	s_waitcnt lgkmcnt(6)
	v_add_f32_e32 v82, v114, v66
	v_add_f32_e32 v83, v115, v67
	s_waitcnt lgkmcnt(4)
	v_add_f32_e32 v86, v118, v74
	v_add_f32_e32 v87, v119, v75
	s_waitcnt lgkmcnt(2)
	v_add_f32_e32 v90, v122, v90
	v_add_f32_e32 v91, v123, v91
	v_add_f32_e32 v80, v112, v64
	v_add_f32_e32 v81, v113, v65
	s_waitcnt lgkmcnt(0)
	v_add_f32_e32 v94, v126, v94
	v_add_f32_e32 v95, v127, v95
	v_add_f32_e32 v84, v116, v72
	v_add_f32_e32 v85, v117, v73
	v_add_f32_e32 v88, v120, v88
	v_add_f32_e32 v89, v121, v89
	v_add_f32_e32 v92, v124, v92
	v_add_f32_e32 v93, v125, v93
	ds_read_b128 v[112:115], v241 offset:480
	v_add_f32_e32 v66, v98, v70
	v_add_f32_e32 v67, v99, v71
	v_add_f32_e32 v70, v102, v78
	v_add_f32_e32 v71, v103, v79
	v_add_f32_e32 v74, v106, v244
	v_add_f32_e32 v75, v107, v245
	v_add_f32_e32 v64, v96, v68
	v_add_f32_e32 v65, v97, v69
	s_waitcnt lgkmcnt(0)
	v_add_f32_e32 v78, v110, v114
	v_add_f32_e32 v79, v111, v115
	v_add_f32_e32 v68, v100, v76
	v_add_f32_e32 v69, v101, v77
	v_add_f32_e32 v72, v104, v242
	v_add_f32_e32 v73, v105, v243
	v_add_f32_e32 v76, v108, v112
	v_add_f32_e32 v77, v109, v113
	s_add_i32 s53, s53, 3
	s_cmp_lt_i32 s53, 0
	s_cbranch_scc1 .LBB0_436
	v_mov_b32_e32 v96, v229
	v_mov_b32_e32 v97, v233
	s_nop 0
	v_lshl_add_u32 v96, v96, 2, s55
	v_subrev_u32_e32 v99, 27, v96
	v_subrev_u32_e32 v98, 59, v96
	v_cmp_le_i32_e32 vcc, v99, v97
	s_nop 1
	v_cndmask_b32_e32 v64, v227, v64, vcc
	v_cmp_lt_i32_e32 vcc, v98, v97
	s_nop 1
	v_cndmask_b32_e32 v81, v227, v81, vcc
	v_cmp_le_i32_e32 vcc, v98, v97
	v_subrev_u32_e32 v98, 26, v96
	s_nop 0
	v_cndmask_b32_e32 v80, v227, v80, vcc
	v_cmp_le_i32_e32 vcc, v98, v97
	v_subrev_u32_e32 v98, 57, v96
	s_nop 0
	v_cndmask_b32_e32 v65, v227, v65, vcc
	v_cmp_le_i32_e32 vcc, v98, v97
	v_subrev_u32_e32 v98, 25, v96
	s_nop 0
	v_cndmask_b32_e32 v82, v227, v82, vcc
	v_cmp_le_i32_e32 vcc, v98, v97
	v_subrev_u32_e32 v98, 56, v96
	s_nop 0
	v_cndmask_b32_e32 v66, v227, v66, vcc
	v_cmp_le_i32_e32 vcc, v98, v97
	v_subrev_u32_e32 v98, 24, v96
	s_nop 0
	v_cndmask_b32_e32 v83, v227, v83, vcc
	v_cmp_le_i32_e32 vcc, v98, v97
	v_subrev_u32_e32 v98, 51, v96
	s_nop 0
	v_cndmask_b32_e32 v67, v227, v67, vcc
	v_cmp_le_i32_e32 vcc, v98, v97
	v_subrev_u32_e32 v98, 19, v96
	s_nop 0
	v_cndmask_b32_e32 v84, v227, v84, vcc
	v_cmp_le_i32_e32 vcc, v98, v97
	v_subrev_u32_e32 v98, 50, v96
	s_nop 0
	v_cndmask_b32_e32 v68, v227, v68, vcc
	v_cmp_le_i32_e32 vcc, v98, v97
	v_subrev_u32_e32 v98, 18, v96
	s_nop 0
	v_cndmask_b32_e32 v85, v227, v85, vcc
	v_cmp_le_i32_e32 vcc, v98, v97
	v_subrev_u32_e32 v98, 49, v96
	s_nop 0
	v_cndmask_b32_e32 v69, v227, v69, vcc
	v_cmp_le_i32_e32 vcc, v98, v97
	v_subrev_u32_e32 v98, 17, v96
	s_nop 0
	v_cndmask_b32_e32 v86, v227, v86, vcc
	v_cmp_le_i32_e32 vcc, v98, v97
	v_subrev_u32_e32 v98, 48, v96
	s_nop 0
	v_cndmask_b32_e32 v70, v227, v70, vcc
	v_cmp_le_i32_e32 vcc, v98, v97
	v_add_u32_e32 v98, -16, v96
	s_nop 0
	v_cndmask_b32_e32 v87, v227, v87, vcc
	v_cmp_le_i32_e32 vcc, v98, v97
	v_subrev_u32_e32 v98, 43, v96
	s_nop 0
	v_cndmask_b32_e32 v71, v227, v71, vcc
	v_cmp_le_i32_e32 vcc, v98, v97
	v_add_u32_e32 v98, -11, v96
	s_nop 0
	v_cndmask_b32_e32 v88, v227, v88, vcc
	v_cmp_le_i32_e32 vcc, v98, v97
	v_subrev_u32_e32 v98, 42, v96
	s_nop 0
	v_cndmask_b32_e32 v72, v227, v72, vcc
	v_cmp_le_i32_e32 vcc, v98, v97
	v_add_u32_e32 v98, -10, v96
	s_nop 0
	v_cndmask_b32_e32 v89, v227, v89, vcc
	v_cmp_le_i32_e32 vcc, v98, v97
	v_subrev_u32_e32 v98, 41, v96
	s_nop 0
	v_cndmask_b32_e32 v73, v227, v73, vcc
	v_cmp_le_i32_e32 vcc, v98, v97
	v_add_u32_e32 v98, -9, v96
	s_nop 0
	v_cndmask_b32_e32 v90, v227, v90, vcc
	v_cmp_le_i32_e32 vcc, v98, v97
	v_subrev_u32_e32 v98, 40, v96
	s_nop 0
	v_cndmask_b32_e32 v74, v227, v74, vcc
	v_cmp_le_i32_e32 vcc, v98, v97
	v_add_u32_e32 v98, -8, v96
	s_nop 0
	v_cndmask_b32_e32 v91, v227, v91, vcc
	v_cmp_le_i32_e32 vcc, v98, v97
	v_subrev_u32_e32 v98, 35, v96
	s_nop 0
	v_cndmask_b32_e32 v75, v227, v75, vcc
	v_cmp_le_i32_e32 vcc, v98, v97
	v_add_u32_e32 v98, -3, v96
	s_nop 0
	v_cndmask_b32_e32 v92, v227, v92, vcc
	v_cmp_le_i32_e32 vcc, v98, v97
	v_subrev_u32_e32 v98, 34, v96
	s_nop 0
	v_cndmask_b32_e32 v76, v227, v76, vcc
	v_cmp_le_i32_e32 vcc, v98, v97
	v_add_u32_e32 v98, -2, v96
	s_nop 0
	v_cndmask_b32_e32 v93, v227, v93, vcc
	v_cmp_le_i32_e32 vcc, v98, v97
	v_subrev_u32_e32 v98, 33, v96
	s_nop 0
	v_cndmask_b32_e32 v77, v227, v77, vcc
	v_cmp_le_i32_e32 vcc, v98, v97
	v_add_u32_e32 v98, -1, v96
	s_nop 0
	v_cndmask_b32_e32 v94, v227, v94, vcc
	v_cmp_le_i32_e32 vcc, v98, v97
	v_subrev_u32_e32 v98, 32, v96
	s_nop 0
	v_cndmask_b32_e32 v78, v227, v78, vcc
	v_cmp_le_i32_e32 vcc, v98, v97
	s_nop 1
	v_cndmask_b32_e32 v95, v227, v95, vcc
	v_cmp_le_i32_e32 vcc, v96, v97
	s_nop 1
	v_cndmask_b32_e32 v79, v227, v79, vcc

.LBB0_470:
	v_add_u32_e32 v0, s97, v236
	ds_read_b64_tr_b16 v[192:193], v0 offset:24576
	ds_read_b64_tr_b16 v[194:195], v0 offset:25088
	v_add_f32_e32 v2, v80, v81
	v_add_f32_e32 v2, v82, v2
	v_add_f32_e32 v2, v83, v2
	v_add_f32_e32 v2, v84, v2
	v_add_f32_e32 v2, v85, v2
	v_cvt_pk_bf16_f32 v156, v80, v81
	v_cvt_pk_bf16_f32 v157, v82, v83
	s_waitcnt lgkmcnt(3)
	v_mfma_f32_32x32x16_bf16 v[96:111], v[188:191], v[144:147], v[48:63]
	ds_read_b64_tr_b16 v[124:125], v0 offset:28672
	ds_read_b64_tr_b16 v[126:127], v0 offset:29184
	s_waitcnt lgkmcnt(4)
	v_mfma_f32_32x32x16_bf16 v[48:63], v[184:187], v[144:147], v[48:63]
	v_add_f32_e32 v2, v86, v2
	v_add_f32_e32 v2, v87, v2
	v_add_f32_e32 v2, v88, v2
	v_add_f32_e32 v2, v89, v2
	v_cvt_pk_bf16_f32 v158, v84, v85
	v_cvt_pk_bf16_f32 v159, v86, v87
	ds_read_b64_tr_b16 v[120:121], v0 offset:25600
	ds_read_b64_tr_b16 v[122:123], v0 offset:26112
	v_add_f32_e32 v2, v90, v2
	v_add_f32_e32 v2, v91, v2
	v_add_f32_e32 v2, v92, v2
	v_add_f32_e32 v2, v93, v2
	v_cvt_pk_bf16_f32 v152, v88, v89
	v_cvt_pk_bf16_f32 v153, v90, v91
	v_mfma_f32_32x32x16_bf16 v[96:111], v[180:183], v[136:139], v[96:111]
	ds_read_b64_tr_b16 v[116:117], v0 offset:29696
	ds_read_b64_tr_b16 v[118:119], v0 offset:30208
	v_mfma_f32_32x32x16_bf16 v[48:63], v[176:179], v[136:139], v[48:63]
	v_add_f32_e32 v2, v94, v2
	v_add_f32_e32 v2, v95, v2
	v_add_f32_e32 v2, v64, v2
	v_add_f32_e32 v2, v65, v2
	v_cvt_pk_bf16_f32 v154, v92, v93
	v_cvt_pk_bf16_f32 v155, v94, v95
	ds_read_b64_tr_b16 v[112:113], v0 offset:26624
	ds_read_b64_tr_b16 v[114:115], v0 offset:27136
	v_add_f32_e32 v2, v66, v2
	v_add_f32_e32 v2, v67, v2
	v_add_f32_e32 v2, v68, v2
	v_add_f32_e32 v2, v69, v2
	v_cvt_pk_bf16_f32 v148, v64, v65
	v_cvt_pk_bf16_f32 v149, v66, v67
	v_mfma_f32_32x32x16_bf16 v[96:111], v[172:175], v[132:135], v[96:111]
	ds_read_b64_tr_b16 v[10:11], v0 offset:30720
	ds_read_b64_tr_b16 v[12:13], v0 offset:31232
	v_mfma_f32_32x32x16_bf16 v[48:63], v[168:171], v[132:135], v[48:63]
	v_add_f32_e32 v2, v70, v2
	v_add_f32_e32 v2, v71, v2
	v_add_f32_e32 v2, v72, v2
	v_add_f32_e32 v2, v73, v2
	v_cvt_pk_bf16_f32 v150, v68, v69
	v_cvt_pk_bf16_f32 v151, v70, v71
	ds_read_b64_tr_b16 v[6:7], v0 offset:27648
	ds_read_b64_tr_b16 v[8:9], v0 offset:28160
	v_add_f32_e32 v2, v74, v2
	v_add_f32_e32 v2, v75, v2
	v_add_f32_e32 v2, v76, v2
	v_add_f32_e32 v14, v77, v2
	v_cvt_pk_bf16_f32 v140, v72, v73
	v_cvt_pk_bf16_f32 v141, v74, v75
	v_mfma_f32_32x32x16_bf16 v[96:111], v[164:167], v[128:131], v[96:111]
	ds_read_b64_tr_b16 v[2:3], v0 offset:31744
	ds_read_b64_tr_b16 v[4:5], v0 offset:32256
	v_mfma_f32_32x32x16_bf16 v[48:63], v[160:163], v[128:131], v[48:63]
	v_add_f32_e32 v0, v78, v14
	v_add_f32_e32 v0, v79, v0
	v_add_f32_e32 v0, 0, v0
	v_cvt_pk_bf16_f32 v142, v76, v77
	v_cvt_pk_bf16_f32 v143, v78, v79
	s_lshl_b32 s8, s95, 2
	s_add_i32 s8, s8, 0
	v_mov_b32_e32 v14, v229
	s_add_i32 s8, s8, 0x14800
	s_nop 0
	v_lshl_add_u32 v94, v14, 4, s8
	v_add_u32_e32 v14, 0xffffff00, v94
	ds_read_b128 v[64:67], v14
	v_add_u32_e32 v14, 0xffffff80, v94
	ds_read_b128 v[68:71], v14
	v_add_u32_e32 v14, 0xffffff20, v94
	ds_read_b128 v[72:75], v14
	v_add_u32_e32 v14, 0xffffffa0, v94
	ds_read_b128 v[76:79], v14
	v_add_u32_e32 v14, 0xffffff40, v94
	ds_read_b128 v[80:83], v14
	v_subrev_u32_e32 v14, 64, v94
	ds_read_b128 v[84:87], v14
	v_add_u32_e32 v14, 0xffffff60, v94
	ds_read_b128 v[88:91], v14
	s_waitcnt lgkmcnt(6)
	v_add_f32_e32 v14, v98, v66
	v_add_f32_e32 v15, v99, v67
	s_waitcnt lgkmcnt(4)
	v_add_f32_e32 v72, v100, v72
	v_add_f32_e32 v73, v101, v73
	v_add_f32_e32 v74, v102, v74
	v_add_f32_e32 v75, v103, v75
	s_waitcnt lgkmcnt(2)
	v_add_f32_e32 v80, v104, v80
	v_add_f32_e32 v81, v105, v81
	v_add_f32_e32 v82, v106, v82
	v_add_f32_e32 v83, v107, v83
	s_waitcnt lgkmcnt(0)
	v_add_f32_e32 v88, v108, v88
	v_add_f32_e32 v89, v109, v89
	v_add_f32_e32 v90, v110, v90
	v_add_f32_e32 v91, v111, v91
	v_add_f32_e32 v92, v96, v64
	v_add_f32_e32 v93, v97, v65
	v_subrev_u32_e32 v64, 32, v94
	ds_read_b128 v[64:67], v64
	v_add_f32_e32 v50, v50, v70
	v_add_f32_e32 v51, v51, v71
	v_add_f32_e32 v52, v52, v76
	v_add_f32_e32 v53, v53, v77
	v_add_f32_e32 v54, v54, v78
	v_add_f32_e32 v55, v55, v79
	v_add_f32_e32 v56, v56, v84
	v_add_f32_e32 v57, v57, v85
	v_add_f32_e32 v58, v58, v86
	v_add_f32_e32 v59, v59, v87
	s_waitcnt lgkmcnt(0)
; __device__ __forceinline__ void cmask(f32x16&p0,f32x16&p1,int jb,int qrel,int hi){
;   const float NEG=-INFINITY; int kb=64*jb+4*hi;
;   #pragma unroll
;   for(int r=0;r<16;++r){int kv=kb+(r&3)+8*(r>>2); if(kv>qrel)p0[r]=NEG; if(kv+32>qrel)p1[r]=NEG;}
; }
	v_add_f32_e32 v60, v60, v64
	v_add_f32_e32 v61, v61, v65
	v_add_f32_e32 v62, v62, v66
	v_add_f32_e32 v63, v63, v67
	v_add_f32_e32 v48, v48, v68
	v_add_f32_e32 v49, v49, v69
	v_mov_b32_e32 v64, v229
	v_add_f32_e32 v0, v238, v0
	v_lshlrev_b32_e32 v84, 2, v64
	v_add_u32_e32 v65, 0xe0, v84
	v_add_u32_e32 v64, 0xc0, v84
	v_cmp_le_i32_e32 vcc, v65, v233
	v_add_u32_e32 v66, 0xe1, v84
	s_nop 0
	v_cndmask_b32_e32 v48, v227, v48, vcc
	v_cmp_lt_i32_e32 vcc, v64, v233
	s_nop 1
	v_cndmask_b32_e32 v65, v227, v93, vcc
	v_cmp_le_i32_e32 vcc, v64, v233
	s_nop 1
	v_cndmask_b32_e32 v64, v227, v92, vcc
	v_cmp_le_i32_e32 vcc, v66, v233
	v_add_u32_e32 v66, 0xc2, v84
	s_nop 0
	v_cndmask_b32_e32 v49, v227, v49, vcc
	v_cmp_le_i32_e32 vcc, v66, v233
	s_nop 1
	v_cndmask_b32_e32 v66, v227, v14, vcc
	v_add_u32_e32 v14, 0xe2, v84
	v_cmp_le_i32_e32 vcc, v14, v233
	v_add_u32_e32 v14, 0xc3, v84
	s_nop 0
	v_cndmask_b32_e32 v50, v227, v50, vcc
	v_cmp_le_i32_e32 vcc, v14, v233
	v_add_u32_e32 v14, 0xe3, v84
	s_nop 0
	v_cndmask_b32_e32 v67, v227, v15, vcc
	v_cmp_le_i32_e32 vcc, v14, v233
	v_add_u32_e32 v14, 0xc8, v84
	v_max3_f32 v15, v66, v67, v49
	v_cndmask_b32_e32 v51, v227, v51, vcc
	v_cmp_le_i32_e32 vcc, v14, v233
	v_add_u32_e32 v14, 0xe8, v84
	s_nop 0
	v_cndmask_b32_e32 v68, v227, v72, vcc
	v_cmp_le_i32_e32 vcc, v14, v233
	v_add_u32_e32 v14, 0xc9, v84
	s_nop 0
	v_cndmask_b32_e32 v52, v227, v52, vcc
	v_cmp_le_i32_e32 vcc, v14, v233
	v_add_u32_e32 v14, 0xe9, v84
	s_nop 0
	v_cndmask_b32_e32 v69, v227, v73, vcc
	v_cmp_le_i32_e32 vcc, v14, v233
	v_add_u32_e32 v14, 0xca, v84
	s_nop 0
	v_cndmask_b32_e32 v53, v227, v53, vcc
	v_cmp_le_i32_e32 vcc, v14, v233
	v_add_u32_e32 v14, 0xea, v84
	s_nop 0
	v_cndmask_b32_e32 v70, v227, v74, vcc
	v_cmp_le_i32_e32 vcc, v14, v233
	v_add_u32_e32 v14, 0xcb, v84
	s_nop 0
	v_cndmask_b32_e32 v54, v227, v54, vcc
	v_cmp_le_i32_e32 vcc, v14, v233
	v_add_u32_e32 v14, 0xeb, v84
	s_nop 0
	v_cndmask_b32_e32 v71, v227, v75, vcc
	v_cmp_le_i32_e32 vcc, v14, v233
	v_add_u32_e32 v14, 0xd0, v84
	v_max3_f32 v15, v15, v70, v71
	v_cndmask_b32_e32 v55, v227, v55, vcc
	v_cmp_le_i32_e32 vcc, v14, v233
	v_add_u32_e32 v14, 0xf0, v84
	v_max3_f32 v15, v15, v54, v55
	v_cndmask_b32_e32 v72, v227, v80, vcc
	v_cmp_le_i32_e32 vcc, v14, v233
	v_add_u32_e32 v14, 0xd1, v84
	s_nop 0
	v_cndmask_b32_e32 v56, v227, v56, vcc
	v_cmp_le_i32_e32 vcc, v14, v233
	v_add_u32_e32 v14, 0xf1, v84
	s_nop 0
	v_cndmask_b32_e32 v73, v227, v81, vcc
	v_cmp_le_i32_e32 vcc, v14, v233
	v_add_u32_e32 v14, 0xd2, v84
	s_nop 0
	v_cndmask_b32_e32 v57, v227, v57, vcc
	v_cmp_le_i32_e32 vcc, v14, v233
	v_add_u32_e32 v14, 0xf2, v84
	s_nop 0
	v_cndmask_b32_e32 v74, v227, v82, vcc
	v_cmp_le_i32_e32 vcc, v14, v233
	v_add_u32_e32 v14, 0xd3, v84
	s_nop 0
	v_cndmask_b32_e32 v58, v227, v58, vcc
	v_cmp_le_i32_e32 vcc, v14, v233
	v_add_u32_e32 v14, 0xf3, v84
	s_nop 0
	v_cndmask_b32_e32 v75, v227, v83, vcc
	v_cmp_le_i32_e32 vcc, v14, v233
	v_add_u32_e32 v14, 0xd8, v84
	v_max3_f32 v15, v15, v74, v75
	v_cndmask_b32_e32 v59, v227, v59, vcc
	v_cmp_le_i32_e32 vcc, v14, v233
	v_add_u32_e32 v14, 0xf8, v84
	v_max3_f32 v15, v15, v58, v59
	v_cndmask_b32_e32 v76, v227, v88, vcc
	v_cmp_le_i32_e32 vcc, v14, v233
	v_add_u32_e32 v14, 0xd9, v84
	s_nop 0
	v_cndmask_b32_e32 v60, v227, v60, vcc
	v_cmp_le_i32_e32 vcc, v14, v233
	v_add_u32_e32 v14, 0xf9, v84
	s_nop 0
	v_cndmask_b32_e32 v77, v227, v89, vcc
	v_cmp_le_i32_e32 vcc, v14, v233
	v_add_u32_e32 v14, 0xda, v84
	s_nop 0
	v_cndmask_b32_e32 v61, v227, v61, vcc
	v_cmp_le_i32_e32 vcc, v14, v233
	v_add_u32_e32 v14, 0xfa, v84
	s_nop 0
	v_cndmask_b32_e32 v78, v227, v90, vcc
	v_cmp_le_i32_e32 vcc, v14, v233
	v_add_u32_e32 v14, 0xdb, v84
	s_nop 0
	v_cndmask_b32_e32 v62, v227, v62, vcc
	v_cmp_le_i32_e32 vcc, v14, v233
	v_add_u32_e32 v14, 0xfb, v84
	s_nop 0
	v_cndmask_b32_e32 v79, v227, v91, vcc
	v_cmp_le_i32_e32 vcc, v14, v233
	v_max_f32_e32 v14, v64, v65
	v_max3_f32 v14, v14, v48, v50
	v_max3_f32 v14, v14, v51, v68
	v_max3_f32 v14, v14, v69, v52
	v_max3_f32 v14, v14, v53, v72
	v_max3_f32 v14, v14, v73, v56
	v_cndmask_b32_e32 v63, v227, v63, vcc
	v_max3_f32 v14, v14, v57, v76
	v_max3_f32 v15, v15, v78, v79
	v_max3_f32 v14, v14, v77, v60
	v_max3_f32 v15, v15, v62, v63
	v_max3_f32 v14, v14, v61, v15
	v_mov_b32_e32 v15, v14
	s_nop 1
	v_permlane32_swap_b32_e32 v14, v15
	v_max_f32_e32 v15, v15, v15
	v_max_f32_e32 v14, v14, v14
	v_max_f32_e32 v14, v14, v15
	v_cmp_lt_f32_e32 vcc, s92, v14
	s_cmp_lg_u64 vcc, 0
	s_cselect_b64 s[8:9], -1, 0
	s_cbranch_vccnz .LBB0_475
